# attention main loop: Q fragment 0 kept resident in registers (first QK MFMAs issue right after the step barrier), on mhat-fold
# baseline (speedup 1.0000x reference)
; #define WAIT_BAR(N) asm volatile("s_waitcnt vmcnt(" #N ") lgkmcnt(0)\n\ts_barrier":::"memory")
;   #define DMA_K(t,slot) glds16(ksrc+(long)(t)*KVBLK*PQ,(unsigned)__builtin_amdgcn_readfirstlane(kdst+(slot)))
;   #define DMA_V(t,slot) glds16(vsrc+(long)(t)*KVBLK*PQ,(unsigned)__builtin_amdgcn_readfirstlane(vdst+(slot)))
;   #define CMASK(P0,P1,t) do{int jb_=(t)-(NT-4); if(jb_>=0)cmask(P0,P1,jb_,qrel,hi);}while(0)
;   #define START(P0,P1) do{ const float rm=rowmax(P0,P1); resc=false; \
;     { const float dl=rm; mhat=fadd_s(mhat,dl); \
;       _Pragma("unroll") for(int r=0;r<16;++r){P0[r]=fsub_s(P0[r],dl);P1[r]=fsub_s(P1[r],dl);} \
;       _Pragma("unroll") for(int r=0;r<16;++r)negm[r]=-mhat; asm volatile("":"+v"(negm)); } \
;     _Pragma("unroll") for(int r=0;r<16;++r)P0[r]=__builtin_amdgcn_exp2f(P0[r]); }while(0)
;   #define CMASK(P0,P1,t) do{}while(0)
;   #define CMASK(P0,P1,t) do{}while(0)
; template<int THRL> __device__ __forceinline__ void attn_unit128(int qb,const bf16*Qh,const bf16*__restrict__ Kh,const bf16*__restrict__ Vh,bf16*Oh,char*shm){
;     ...
;   const int vb0=(int)(lds0+L_V)+((lane>>4)&1)*32+(lane&3)*8+(4*hi+((lane&15)>>2))*64;
;   const char*Kbase=shm+L_K; bf16x8 kf[8];
;   const lds_cptr shm3=(lds_cptr)shm; const lds_cptr kp0=shm3+L_K+hi*1024+r32*16; const lds_cptr vp0=shm3+L_V+((lane>>4)&1)*32+(lane&3)*8+(4*hi+((lane&15)>>2))*64;
;   const lds_cptr qp=shm3+L_Q+wid*4096+lane*16;
;     ...
;   const int NT=(q0+QB)/KVBLK;
;   DMA_K(0,0);DMA_V(0,0);DMA_K(1,KSLOT);
;   #pragma unroll
;   for(int d0=0;d0<4;++d0)glds16(&Qw[(long)r32*PQ+d0*16+hi*8],(unsigned)__builtin_amdgcn_readfirstlane(qdst+d0*1024));
;   float mhat=0.f,l_reg=0.f;f32x16 o[4];o[0]=f32x16{};o[1]=f32x16{};o[2]=f32x16{};o[3]=f32x16{};
;   const f32x16 zero16=f32x16{};
;   const int qrel=wid*QBLK+r32;
;     ...
;   bool resc=false;
;     ...
;   f32x16 pA0,pA1,pB0,pB1;
;   int sl_prev=0,sl_cur=0,sl_next=KSLOT;
;     ...
;   DMA_K(2,2*KSLOT);
;   WAIT_BAR(1);
;   { bf16x8 q4[4];
;     #pragma unroll
;     for(int d0=0;d0<4;++d0)q4[d0]=QLD(d0);
;     qkt(pA0,pA1,Kbase,q4,zero16,r32,hi); }
;   asm volatile("s_nop 15\n\ts_nop 7":"+v"(pA0),"+v"(pA1));CMASK(pA0,pA1,0);
;   START(pA0,pA1);
;   _Pragma("unroll") for(int r=0;r<16;++r)pA1[r]=__builtin_amdgcn_exp2f(pA1[r]);
;   WAIT_BAR(0);
;   DMA_K(3,0);DMA_V(1,KSLOT);
;   ROT();
;   kload8(kf,kp0+sl_cur);
;   WAIT_BAR(3);
;   s16x4 vlo[16],vhi[16]; u32x4 pw0,pw1,pw2,pw3;
.LBB0_367:
	v_lshlrev_b32_e32 v35, 1, v34
	v_lshlrev_b32_e32 v215, 3, v34
	v_lshlrev_b32_e32 v34, 4, v34
	v_and_b32_e32 v218, 32, v35
	v_and_b32_e32 v34, 0xc0, v34
	v_and_b32_e32 v219, 24, v215
	v_lshl_or_b32 v217, v186, 8, v34
	v_add_u32_e32 v34, 0, v218
	v_add3_u32 v224, v34, v219, v217
	v_max3_f32 v34, v0, v1, v16
	v_max3_f32 v35, v2, v3, v17
	s_and_b32 s1, s1, 0x3fffffc0
	v_max3_f32 v34, v34, v18, v19
	v_max3_f32 v35, v35, v6, v7
	s_lshl_b32 s1, s1, 2
	v_max3_f32 v34, v34, v4, v5
	v_max3_f32 v35, v35, v22, v23
	s_add_i32 s34, s1, 0
	v_max3_f32 v34, v34, v20, v21
	v_max3_f32 v35, v35, v10, v11
	s_add_i32 s34, s34, 0x12000
	v_max3_f32 v34, v34, v8, v9
	v_max3_f32 v35, v35, v26, v27
	s_waitcnt vmcnt(0) lgkmcnt(0)
	s_barrier
	s_cmp_lg_u32 0, -1
	v_max3_f32 v34, v34, v24, v25
	v_max3_f32 v35, v35, v14, v15
	s_mov_b32 s72, 1
	v_max3_f32 v34, v34, v12, v13
	v_max3_f32 v35, v35, v30, v31
	s_mov_b32 s28, 0
	v_max3_f32 v34, v34, v28, v29
	v_lshlrev_b32_e32 v225, 4, v186
	v_max_f32_e32 v34, v34, v35
	v_lshl_add_u32 v216, v213, 2, s34
	v_mov_b32_e32 v35, v34
	s_nop 1
	v_permlane32_swap_b32_e32 v34, v35
	v_max_f32_e32 v34, v34, v35
	s_nop 0
	v_sub_f32_e32 v0, v0, v34
	v_sub_f32_e32 v1, v1, v34
	v_sub_f32_e32 v16, v16, v34
	v_sub_f32_e32 v17, v17, v34
	v_sub_f32_e32 v2, v2, v34
	v_sub_f32_e32 v18, v18, v34
	s_nop 0
	v_exp_f32_e32 v80, v0
	v_exp_f32_e32 v81, v1
	v_lshl_add_u64 v[0:1], v[180:181], 0, s[88:89]
	s_mov_b32 s1, m0
	s_mov_b32 m0, s42
	s_nop 0
	global_load_lds_dwordx4 v[0:1], off
	s_mov_b32 m0, s1
	s_cselect_b32 s1, 0, 0
	s_add_i32 s0, s1, s0
	v_lshl_add_u64 v[0:1], v[32:33], 0, s[86:87]
	s_add_i32 s1, s0, 0xa000
	s_mov_b32 s19, m0
	s_mov_b32 m0, s1
	s_nop 0
	global_load_lds_dwordx4 v[0:1], off
	s_mov_b32 m0, s19
	v_lshl_add_u64 v[0:1], v[32:33], 0, s[88:89]
	s_add_i32 s0, s0, 0xc000
	s_mov_b32 s1, m0
	s_mov_b32 m0, s0
	s_nop 0
	global_load_lds_dwordx4 v[0:1], off
	s_mov_b32 m0, s1
	ds_read_b128 v[168:171], v223 offset:8192
	ds_read_b128 v[160:163], v223 offset:8704
	ds_read_b128 v[172:175], v223 offset:10240
	ds_read_b128 v[156:159], v223 offset:10752
	ds_read_b128 v[164:167], v223 offset:12288
	ds_read_b128 v[148:151], v223 offset:12800
	ds_read_b128 v[152:155], v223 offset:14336
	ds_read_b128 v[144:147], v223 offset:14848
	v_sub_f32_e32 v3, v3, v34
	v_sub_f32_e32 v19, v19, v34
	v_sub_f32_e32 v4, v4, v34
	v_sub_f32_e32 v20, v20, v34
	v_sub_f32_e32 v5, v5, v34
	v_sub_f32_e32 v21, v21, v34
	v_sub_f32_e32 v6, v6, v34
	v_sub_f32_e32 v22, v22, v34
	v_sub_f32_e32 v7, v7, v34
	v_sub_f32_e32 v23, v23, v34
	v_sub_f32_e32 v8, v8, v34
	v_sub_f32_e32 v24, v24, v34
	v_sub_f32_e32 v9, v9, v34
	v_sub_f32_e32 v25, v25, v34
	v_sub_f32_e32 v10, v10, v34
	v_sub_f32_e32 v26, v26, v34
	v_sub_f32_e32 v11, v11, v34
	v_sub_f32_e32 v27, v27, v34
	v_sub_f32_e32 v12, v12, v34
	v_sub_f32_e32 v28, v28, v34
	v_sub_f32_e32 v13, v13, v34
	v_sub_f32_e32 v29, v29, v34
	v_sub_f32_e32 v14, v14, v34
	v_sub_f32_e32 v30, v30, v34
	v_sub_f32_e32 v15, v15, v34
	v_sub_f32_e32 v31, v31, v34
	v_exp_f32_e32 v82, v2
	v_exp_f32_e32 v83, v3
	v_exp_f32_e32 v84, v4
	v_exp_f32_e32 v85, v5
	v_exp_f32_e32 v86, v6
	v_exp_f32_e32 v87, v7
	v_exp_f32_e32 v88, v8
	v_exp_f32_e32 v89, v9
	v_exp_f32_e32 v90, v10
	v_exp_f32_e32 v91, v11
	v_exp_f32_e32 v92, v12
	v_exp_f32_e32 v93, v13
	v_exp_f32_e32 v94, v14
	v_exp_f32_e32 v95, v15
	v_exp_f32_e32 v64, v16
	v_exp_f32_e32 v65, v17
	v_exp_f32_e32 v66, v18
	v_exp_f32_e32 v67, v19
	v_exp_f32_e32 v68, v20
	v_exp_f32_e32 v69, v21
	v_exp_f32_e32 v70, v22
	v_exp_f32_e32 v71, v23
	v_exp_f32_e32 v72, v24
	v_exp_f32_e32 v73, v25
	v_exp_f32_e32 v74, v26
	v_exp_f32_e32 v75, v27
	v_exp_f32_e32 v76, v28
	v_exp_f32_e32 v77, v29
	v_exp_f32_e32 v78, v30
	v_exp_f32_e32 v79, v31
	s_waitcnt vmcnt(3) lgkmcnt(0)
	s_barrier
	s_andn2_b64 vcc, exec, s[16:17]
	v_cmp_gt_u32_e64 s[0:1], 32, v212
	v_add_f32_e32 v220, v195, v34
	s_cbranch_vccnz .LBB0_383
	s_add_u32 s20, s59, s24
	s_addc_u32 s21, s60, s25
	v_mov_b32_e32 v32, v195
	v_mov_b32_e32 v33, v195
	v_mov_b32_e32 v46, v195
	v_mov_b32_e32 v47, v195
	v_lshl_add_u64 v[182:183], s[20:21], 0, v[194:195]
	s_mov_b64 s[20:21], 0xa000
	v_mov_b32_e32 v34, v195
	v_mov_b32_e32 v35, v195
	v_mov_b32_e32 v36, v195
	v_mov_b32_e32 v37, v195
	v_mov_b32_e32 v38, v195
	v_mov_b32_e32 v39, v195
	v_mov_b32_e32 v40, v195
	v_mov_b32_e32 v41, v195
	v_mov_b32_e32 v42, v195
	v_mov_b32_e32 v43, v195
	v_mov_b32_e32 v44, v195
	v_mov_b32_e32 v45, v195
	v_mov_b64_e32 v[62:63], v[46:47]
	v_mov_b64_e32 v[16:17], v[32:33]
	v_mov_b64_e32 v[0:1], v[32:33]
	v_lshl_add_u64 v[184:185], v[180:181], 0, s[20:21]
	s_mov_b32 s20, 0
	s_movk_i32 s28, 0x4000
	s_movk_i32 s29, 0x2000
	v_mov_b32_e32 v226, 0
	s_mov_b32 s19, 6
	v_mov_b64_e32 v[60:61], v[44:45]
	v_mov_b64_e32 v[58:59], v[42:43]
	v_mov_b64_e32 v[56:57], v[40:41]
	v_mov_b64_e32 v[54:55], v[38:39]
	v_mov_b64_e32 v[52:53], v[36:37]
	v_mov_b64_e32 v[50:51], v[34:35]
	v_mov_b64_e32 v[48:49], v[32:33]
	v_mov_b64_e32 v[18:19], v[34:35]
	v_mov_b64_e32 v[20:21], v[36:37]
	v_mov_b64_e32 v[22:23], v[38:39]
	v_mov_b64_e32 v[24:25], v[40:41]
	v_mov_b64_e32 v[26:27], v[42:43]
	v_mov_b64_e32 v[28:29], v[44:45]
	v_mov_b64_e32 v[30:31], v[46:47]
	v_mov_b64_e32 v[2:3], v[34:35]
	v_mov_b64_e32 v[4:5], v[36:37]
	v_mov_b64_e32 v[6:7], v[38:39]
	v_mov_b64_e32 v[8:9], v[40:41]
	v_mov_b64_e32 v[10:11], v[42:43]
	v_mov_b64_e32 v[12:13], v[44:45]
	v_mov_b64_e32 v[14:15], v[46:47]
	v_add_u32_e32 v204, 0xfffed800, v222
	v_bfe_u32 v205, v204, 4, 6
	v_and_b32_e32 v189, 0xfffff000, v204
	v_lshl_add_u32 v189, v205, 2, v189
	s_movk_i32 s100, 0x4fff
	v_cmp_lt_u32_e64 s[98:99], s100, v204
	v_mov_b32_e32 v205, 0x1200
	v_cndmask_b32_e64 v204, 0, v205, s[98:99]
	v_add_u32_e32 v189, v189, v204
	v_add_u32_e32 v189, 0x1a800, v189
	ds_write_b32 v189, v192
	ds_write_b32 v189, v193 offset:256
	ds_write_b32 v189, v194 offset:512
	ds_write_b32 v189, v195 offset:768
	ds_write_b32 v189, v196 offset:1024
	ds_write_b32 v189, v197 offset:1280
	ds_write_b32 v189, v198 offset:1536
	ds_write_b32 v189, v199 offset:1792
	ds_write_b32 v189, v200 offset:2048
	ds_write_b32 v189, v201 offset:2304
	ds_write_b32 v189, v202 offset:2560
	ds_write_b32 v189, v203 offset:2816
	ds_write_b32 v189, v206 offset:3072
	ds_write_b32 v189, v207 offset:3328
	ds_write_b32 v189, v254 offset:3584
	ds_write_b32 v189, v255 offset:3840
	s_waitcnt lgkmcnt(0)
	ds_read_b128 v[252:255], v222
	v_sub_f32_e32 v192, 0, v220
	v_sub_f32_e32 v193, 0, v220
	v_sub_f32_e32 v194, 0, v220
	v_sub_f32_e32 v195, 0, v220
	v_sub_f32_e32 v196, 0, v220
	v_sub_f32_e32 v197, 0, v220
	v_sub_f32_e32 v198, 0, v220
	v_sub_f32_e32 v199, 0, v220
	v_sub_f32_e32 v200, 0, v220
	v_sub_f32_e32 v201, 0, v220
	v_sub_f32_e32 v202, 0, v220
	v_sub_f32_e32 v203, 0, v220
	v_sub_f32_e32 v204, 0, v220
	v_sub_f32_e32 v205, 0, v220
	v_sub_f32_e32 v206, 0, v220
	v_sub_f32_e32 v207, 0, v220
	s_waitcnt lgkmcnt(0)
.LBB0_369:
	s_lshl_b32 s20, s20, 1
	v_add_u32_e32 v187, s20, v224
	ds_read_b128 v[228:231], v222 offset:1024
	ds_read_b128 v[232:235], v222 offset:2048
	ds_read_b128 v[248:251], v222 offset:3072
	ds_read_b64_tr_b16 v[176:177], v187 offset:24576
	ds_read_b64_tr_b16 v[178:179], v187 offset:25088
	s_waitcnt lgkmcnt(5)
	v_mfma_f32_32x32x16_bf16 v[112:127], v[168:171], v[252:255], v[192:207]
	v_add_f32_e32 v100, v80, v81
	v_add_f32_e32 v100, v82, v100
	v_add_f32_e32 v100, v83, v100
	v_add_f32_e32 v100, v84, v100
	v_add_f32_e32 v100, v85, v100
	v_cvt_pk_bf16_f32 v140, v80, v81
	v_cvt_pk_bf16_f32 v141, v82, v83
	ds_read_b64_tr_b16 v[168:169], v187 offset:28672
	ds_read_b64_tr_b16 v[170:171], v187 offset:29184
	v_add_f32_e32 v80, v86, v100
	v_mfma_f32_32x32x16_bf16 v[96:111], v[160:163], v[252:255], v[192:207]
	v_add_f32_e32 v80, v87, v80
	v_add_f32_e32 v80, v88, v80
	v_add_f32_e32 v80, v89, v80
	v_cvt_pk_bf16_f32 v142, v84, v85
	v_cvt_pk_bf16_f32 v143, v86, v87
	ds_read_b64_tr_b16 v[84:85], v187 offset:32768
	ds_read_b64_tr_b16 v[86:87], v187 offset:33280
	s_waitcnt lgkmcnt(8)
	v_mfma_f32_32x32x16_bf16 v[112:127], v[172:175], v[228:231], v[112:127]
	v_add_f32_e32 v80, v90, v80
	v_add_f32_e32 v80, v91, v80
	v_add_f32_e32 v80, v92, v80
	v_add_f32_e32 v128, v93, v80
	v_cvt_pk_bf16_f32 v136, v88, v89
	v_cvt_pk_bf16_f32 v137, v90, v91
	ds_read_b64_tr_b16 v[80:81], v187 offset:36864
	ds_read_b64_tr_b16 v[82:83], v187 offset:37376
	v_mfma_f32_32x32x16_bf16 v[96:111], v[156:159], v[228:231], v[96:111]
	v_add_f32_e32 v88, v94, v128
	v_add_f32_e32 v88, v95, v88
	v_add_f32_e32 v88, v64, v88
	v_add_f32_e32 v88, v65, v88
	v_cvt_pk_bf16_f32 v138, v92, v93
	v_cvt_pk_bf16_f32 v139, v94, v95
	ds_read_b64_tr_b16 v[92:93], v187 offset:25600
	ds_read_b64_tr_b16 v[94:95], v187 offset:26112
	s_waitcnt lgkmcnt(11)
	v_mfma_f32_32x32x16_bf16 v[112:127], v[164:167], v[232:235], v[112:127]
	v_add_f32_e32 v88, v66, v88
	v_add_f32_e32 v88, v67, v88
	v_add_f32_e32 v88, v68, v88
	v_add_f32_e32 v128, v69, v88
	v_cvt_pk_bf16_f32 v132, v64, v65
	v_cvt_pk_bf16_f32 v133, v66, v67
	ds_read_b64_tr_b16 v[88:89], v187 offset:29696
	ds_read_b64_tr_b16 v[90:91], v187 offset:30208
	v_mfma_f32_32x32x16_bf16 v[96:111], v[148:151], v[232:235], v[96:111]
	v_add_f32_e32 v64, v70, v128
	v_add_f32_e32 v64, v71, v64
	v_add_f32_e32 v64, v72, v64
	v_add_f32_e32 v64, v73, v64
	v_cvt_pk_bf16_f32 v134, v68, v69
	v_cvt_pk_bf16_f32 v135, v70, v71
	ds_read_b64_tr_b16 v[68:69], v187 offset:33792
	ds_read_b64_tr_b16 v[70:71], v187 offset:34304
	s_waitcnt lgkmcnt(14)
	v_mfma_f32_32x32x16_bf16 v[112:127], v[152:155], v[248:251], v[112:127]
	v_add_f32_e32 v64, v74, v64
	v_add_f32_e32 v64, v75, v64
	v_add_f32_e32 v64, v76, v64
	v_add_f32_e32 v148, v77, v64
	v_cvt_pk_bf16_f32 v128, v72, v73
	v_cvt_pk_bf16_f32 v129, v74, v75
	ds_read_b64_tr_b16 v[64:65], v187 offset:37888
	ds_read_b64_tr_b16 v[66:67], v187 offset:38400
	v_mfma_f32_32x32x16_bf16 v[96:111], v[144:147], v[248:251], v[96:111]
	v_add_f32_e32 v72, v78, v148
	v_add_f32_e32 v72, v79, v72
	v_add_f32_e32 v74, 0, v72
	v_cvt_pk_bf16_f32 v130, v76, v77
	v_cvt_pk_bf16_f32 v131, v78, v79
	v_lshl_add_u64 v[72:73], v[184:185], 0, s[90:91]
	s_add_i32 s20, s29, s42
	s_mov_b32 s21, m0
	s_mov_b32 m0, s20
	s_nop 0
	global_load_lds_dwordx4 v[72:73], off
	s_mov_b32 m0, s21
	s_movk_i32 s20, 0xc000
	s_mov_b32 s21, -1
	v_lshl_add_u64 v[72:73], v[182:183], 0, s[20:21]
	s_lshl_b32 s20, s28, 1
	s_add_i32 s20, s20, s43
	s_mov_b32 s21, m0
	s_mov_b32 m0, s20
	s_nop 0
	global_load_lds_dwordx4 v[72:73], off
	s_mov_b32 m0, s21
	v_lshl_add_u64 v[72:73], v[182:183], 0, s[90:91]
	s_addk_i32 s20, 0x2000
	s_mov_b32 s21, m0
	s_mov_b32 m0, s20
	s_nop 0
	global_load_lds_dwordx4 v[72:73], off
	s_mov_b32 m0, s21
	v_max_f32_e32 v72, v113, v113
	v_max_f32_e32 v73, v112, v112
	v_max_f32_e32 v72, v73, v72
	v_max3_f32 v73, v114, v115, v97
	v_max3_f32 v72, v72, v96, v98
	v_max3_f32 v72, v72, v99, v116
	v_max3_f32 v73, v73, v118, v119
	v_max3_f32 v72, v72, v117, v100
	v_max3_f32 v73, v73, v102, v103
	v_max3_f32 v72, v72, v101, v120
	v_max3_f32 v73, v73, v122, v123
	v_max3_f32 v72, v72, v121, v104
	v_max3_f32 v73, v73, v106, v107
	v_max3_f32 v72, v72, v105, v124
	v_max3_f32 v73, v73, v126, v127
	v_max3_f32 v72, v72, v125, v108
	v_max3_f32 v73, v73, v110, v111
	v_max3_f32 v72, v72, v109, v73
	v_mov_b32_e32 v73, v72
	s_nop 1
	v_permlane32_swap_b32_e32 v72, v73
	v_max_f32_e32 v73, v73, v73
	v_max_f32_e32 v72, v72, v72
	v_max_f32_e32 v72, v72, v73
	v_cmp_lt_f32_e32 vcc, s92, v72
	s_cmp_lg_u64 vcc, 0
	v_add_f32_e32 v190, v226, v74
	s_cselect_b64 s[20:21], -1, 0
	s_cbranch_vccnz .LBB0_377

.LBB0_372:
	s_add_i32 s20, s28, 0x2000
	s_cmpk_lg_i32 s28, 0x4000
	s_cselect_b32 s97, s20, 0
	s_lshl_b32 s20, s29, 1
	v_add_u32_e32 v191, s20, v224
	ds_read_b128 v[226:229], v222 offset:1024
	ds_read_b128 v[230:233], v222 offset:2048
	ds_read_b128 v[234:237], v222 offset:3072
	ds_read_b64_tr_b16 v[176:177], v191 offset:24576
	ds_read_b64_tr_b16 v[178:179], v191 offset:25088
	s_waitcnt lgkmcnt(5)
	v_mfma_f32_32x32x16_bf16 v[80:95], v[68:71], v[252:255], v[192:207]
	v_add_f32_e32 v76, v112, v113
	v_add_f32_e32 v76, v114, v76
	v_add_f32_e32 v76, v115, v76
	v_add_f32_e32 v76, v116, v76
	v_add_f32_e32 v76, v117, v76
	v_cvt_pk_bf16_f32 v140, v112, v113
	v_cvt_pk_bf16_f32 v141, v114, v115
	ds_read_b64_tr_b16 v[172:173], v191 offset:28672
	ds_read_b64_tr_b16 v[174:175], v191 offset:29184
	v_add_f32_e32 v68, v118, v76
	v_add_f32_e32 v68, v119, v68
	v_add_f32_e32 v68, v120, v68
	v_add_f32_e32 v112, v121, v68
	v_mfma_f32_32x32x16_bf16 v[64:79], v[64:67], v[252:255], v[192:207]
	v_cvt_pk_bf16_f32 v142, v116, v117
	v_cvt_pk_bf16_f32 v143, v118, v119
	ds_read_b64_tr_b16 v[168:169], v191 offset:32768
	ds_read_b64_tr_b16 v[170:171], v191 offset:33280
	s_waitcnt lgkmcnt(8)
	v_mfma_f32_32x32x16_bf16 v[80:95], v[164:167], v[226:229], v[80:95]
	v_add_f32_e32 v112, v122, v112
	v_add_f32_e32 v112, v123, v112
	v_add_f32_e32 v112, v124, v112
	v_add_f32_e32 v112, v125, v112
	v_cvt_pk_bf16_f32 v136, v120, v121
	v_cvt_pk_bf16_f32 v137, v122, v123
	ds_read_b64_tr_b16 v[120:121], v191 offset:36864
	ds_read_b64_tr_b16 v[122:123], v191 offset:37376
	v_mfma_f32_32x32x16_bf16 v[64:79], v[152:155], v[226:229], v[64:79]
	v_add_f32_e32 v112, v126, v112
	v_add_f32_e32 v112, v127, v112
	v_add_f32_e32 v112, v96, v112
	v_add_f32_e32 v112, v97, v112
	v_cvt_pk_bf16_f32 v138, v124, v125
	v_cvt_pk_bf16_f32 v139, v126, v127
	ds_read_b64_tr_b16 v[116:117], v191 offset:25600
	ds_read_b64_tr_b16 v[118:119], v191 offset:26112
	s_waitcnt lgkmcnt(11)
	v_mfma_f32_32x32x16_bf16 v[80:95], v[160:163], v[230:233], v[80:95]
	v_add_f32_e32 v112, v98, v112
	v_add_f32_e32 v112, v99, v112
	v_add_f32_e32 v112, v100, v112
	v_add_f32_e32 v124, v101, v112
	v_cvt_pk_bf16_f32 v132, v96, v97
	v_cvt_pk_bf16_f32 v133, v98, v99
	ds_read_b64_tr_b16 v[112:113], v191 offset:29696
	ds_read_b64_tr_b16 v[114:115], v191 offset:30208
	v_mfma_f32_32x32x16_bf16 v[64:79], v[148:151], v[230:233], v[64:79]
	v_add_f32_e32 v96, v102, v124
	v_add_f32_e32 v96, v103, v96
	v_add_f32_e32 v96, v104, v96
	v_add_f32_e32 v96, v105, v96
	v_cvt_pk_bf16_f32 v134, v100, v101
	v_cvt_pk_bf16_f32 v135, v102, v103
	ds_read_b64_tr_b16 v[100:101], v191 offset:33792
	ds_read_b64_tr_b16 v[102:103], v191 offset:34304
	s_waitcnt lgkmcnt(14)
	v_mfma_f32_32x32x16_bf16 v[80:95], v[156:159], v[234:237], v[80:95]
	v_add_f32_e32 v96, v106, v96
	v_add_f32_e32 v96, v107, v96
	v_add_f32_e32 v96, v108, v96
	v_add_f32_e32 v124, v109, v96
	v_cvt_pk_bf16_f32 v128, v104, v105
	v_cvt_pk_bf16_f32 v129, v106, v107
	ds_read_b64_tr_b16 v[96:97], v191 offset:37888
	ds_read_b64_tr_b16 v[98:99], v191 offset:38400
	v_mfma_f32_32x32x16_bf16 v[64:79], v[144:147], v[234:237], v[64:79]
	v_add_f32_e32 v104, v110, v124
	v_add_f32_e32 v104, v111, v104
	v_add_f32_e32 v106, 0, v104
	v_cvt_pk_bf16_f32 v130, v108, v109
	v_cvt_pk_bf16_f32 v131, v110, v111
	s_add_i32 s20, s28, s42
	s_mov_b32 s21, m0
	s_mov_b32 m0, s20
	s_nop 0
	global_load_lds_dwordx4 v[184:185], off
	s_mov_b32 m0, s21
	s_lshl_b32 s20, s97, 1
	s_add_i32 s20, s20, s43
	s_mov_b32 s21, m0
	s_mov_b32 m0, s20
	s_nop 0
	global_load_lds_dwordx4 v[182:183], off
	s_mov_b32 m0, s21
	v_lshl_add_u64 v[104:105], v[182:183], 0, s[84:85]
	s_addk_i32 s20, 0x2000
	s_mov_b32 s21, m0
	s_mov_b32 m0, s20
	s_nop 0
	global_load_lds_dwordx4 v[104:105], off
	s_mov_b32 m0, s21
	v_max_f32_e32 v104, v81, v81
	v_max_f32_e32 v105, v80, v80
	v_max_f32_e32 v104, v105, v104
	v_max3_f32 v105, v82, v83, v65
	v_max3_f32 v104, v104, v64, v66
	v_max3_f32 v104, v104, v67, v84
	v_max3_f32 v105, v105, v86, v87
	v_max3_f32 v104, v104, v85, v68
	v_max3_f32 v105, v105, v70, v71
	v_max3_f32 v104, v104, v69, v88
	v_max3_f32 v105, v105, v90, v91
	v_max3_f32 v104, v104, v89, v72
	v_max3_f32 v105, v105, v74, v75
	v_max3_f32 v104, v104, v73, v92
	v_max3_f32 v105, v105, v94, v95
	v_max3_f32 v104, v104, v93, v76
	v_max3_f32 v105, v105, v78, v79
	v_max3_f32 v104, v104, v77, v105
	v_mov_b32_e32 v105, v104
	s_nop 1
	v_permlane32_swap_b32_e32 v104, v105
	v_max_f32_e32 v105, v105, v105
	v_max_f32_e32 v104, v104, v104
	v_max_f32_e32 v104, v104, v105
	v_cmp_lt_f32_e32 vcc, s92, v104
	s_cmp_lg_u64 vcc, 0
	v_add_f32_e32 v226, v190, v106
	s_cselect_b64 s[20:21], -1, 0
	s_cbranch_vccnz .LBB0_380

; #define WAIT_BAR(N) asm volatile("s_waitcnt vmcnt(" #N ") lgkmcnt(0)\n\ts_barrier":::"memory")
;   #define RESC() do{ if(resc){ asm volatile("s_waitcnt lgkmcnt(0)":::"memory"); \
;       _Pragma("unroll") for(int d_=0;d_<2;++d_) _Pragma("unroll") for(int r=0;r<16;++r)o[d_][r]*=wsf[crow(r,hi)]; } }while(0)
;   #define ROT() do{sl_prev=sl_cur;sl_cur=sl_next;sl_next=(sl_next==(NSLOT-1)*SLOTB)?0:sl_next+SLOTB;}while(0)
;   #define ENDW(tt) do{ if((tt)+3<NT){WAIT_BAR(2);} else if((tt)+2<NT){WAIT_BAR(1);} else {WAIT_BAR(0);} }while(0)
; #define WAIT_BAR(N) asm volatile("s_waitcnt vmcnt(" #N ") lgkmcnt(0)\n\ts_barrier":::"memory")
;   #define RESC() do{ if(resc){ asm volatile("s_waitcnt lgkmcnt(0)":::"memory"); \
;       _Pragma("unroll") for(int d_=0;d_<4;++d_) _Pragma("unroll") for(int r=0;r<16;++r)o[d_][r]*=wsf[crow(r,hi)]; } }while(0)
;   #define ROT() do{sl_prev=sl_cur;sl_cur=sl_next;sl_next=(sl_next==(NSLOT-1)*KSLOT)?0:sl_next+KSLOT;}while(0)
;   #define ENDW(tt) do{ if((tt)+3<NT){WAIT_BAR(3);} else if((tt)+2<NT){WAIT_BAR(2);} else {WAIT_BAR(0);} }while(0)
; template<int THRL> __device__ __forceinline__ void attn_unit128(int qb,const bf16*Qh,const bf16*__restrict__ Kh,const bf16*__restrict__ Vh,bf16*Oh,char*shm){
;     ...
;   for(;t+5<NT;t+=2){
;     STEP(pB0,pB1,pA0,pA1,t,true,true,true);     WAIT_BAR(3); RESC(); ROT();
;     STEP(pA0,pA1,pB0,pB1,t+1,true,true,true);   WAIT_BAR(3); RESC(); ROT();
;   }
;     ...
;   for(;t+1<NT;t+=2){
;     STEP(pB0,pB1,pA0,pA1,t,(t+3<NT),(t+1<NT),(t+1<NT));       ENDW(t);   RESC(); ROT();
;     STEP(pA0,pA1,pB0,pB1,t+1,(t+4<NT),(t+2<NT),(t+2<NT));     ENDW(t+1); RESC(); ROT();
;   }
;   STEP(pB0,pB1,pA0,pA1,NT-1,false,false,false); RESC();
.LBB0_384:
	v_add_u32_e32 v204, 0xfffed800, v222
	v_bfe_u32 v205, v204, 4, 6
	v_and_b32_e32 v189, 0xfffff000, v204
	v_lshl_add_u32 v189, v205, 2, v189
	s_movk_i32 s100, 0x4fff
	v_cmp_lt_u32_e64 s[98:99], s100, v204
	v_mov_b32_e32 v205, 0x1200
	v_cndmask_b32_e64 v204, 0, v205, s[98:99]
	v_add_u32_e32 v189, v189, v204
	v_add_u32_e32 v189, 0x1a800, v189
	ds_read_b32 v192, v189
	ds_read_b32 v193, v189 offset:256
	ds_read_b32 v194, v189 offset:512
	ds_read_b32 v195, v189 offset:768
	ds_read_b32 v196, v189 offset:1024
	ds_read_b32 v197, v189 offset:1280
	ds_read_b32 v198, v189 offset:1536
	ds_read_b32 v199, v189 offset:1792
	ds_read_b32 v200, v189 offset:2048
	ds_read_b32 v201, v189 offset:2304
	ds_read_b32 v202, v189 offset:2560
	ds_read_b32 v203, v189 offset:2816
	ds_read_b32 v206, v189 offset:3072
	ds_read_b32 v207, v189 offset:3328
	ds_read_b32 v254, v189 offset:3584
	ds_read_b32 v255, v189 offset:3840
	s_waitcnt lgkmcnt(0)
	s_add_i32 s72, s19, -3
